# phase 11: NSA-q projection tiles handed out by per-XCD tickets; the 256 WGs owning the long-K compression tiles join that work afterwards (work sharing), on top of v_rot2
# speedup vs baseline: 1.0089x; 1.0089x over previous
.Lp11_join:
	s_add_u32 s100, s72, 0x2f80000
	s_addc_u32 s101, s73, 0
	v_cmp_eq_u32_e32 vcc, 0, v220
	s_and_saveexec_b64 s[10:11], vcc
	s_cbranch_execz .Lp11_tka
	s_and_b32 s4, s2, 7
	s_lshl_b32 s4, s4, 6
	s_add_i32 s4, s4, 32
	v_mov_b32_e32 v2, s4
	v_mov_b32_e32 v1, 1
	global_atomic_add v1, v2, v1, s[100:101] sc0
	s_waitcnt vmcnt(0)
	v_mov_b32_e32 v2, 0x10608
	ds_write_b32 v2, v1
	s_waitcnt lgkmcnt(0)
.Lp11_tka:
	s_or_b64 exec, exec, s[10:11]
	s_barrier
	v_mov_b32_e32 v1, 0x10608
	ds_read_b32 v1, v1
	s_waitcnt lgkmcnt(0)
	s_nop 1
	v_readfirstlane_b32 s4, v1
	s_nop 3
	s_lshl_b32 s4, s4, 3
	s_and_b32 s10, s2, 7
	s_or_b32 s4, s4, s10
	s_cmpk_gt_i32 s4, 0x87f
	s_cbranch_scc1 .LBB0_962
	s_sub_i32 s5, s74, s3
	s_add_u32 s6, s72, 0x1b200000
	s_addc_u32 s7, s73, 0
	s_add_u32 s8, s72, 0x1a20000
	s_addc_u32 s9, s73, 0
	s_add_u32 s0, s72, 0x7040000
	s_addc_u32 s1, s73, 0
	s_add_u32 s22, s72, 0x13200000
	s_addc_u32 s23, s73, 0
	s_waitcnt vmcnt(9)
	v_mov_b32_e32 v153, 0
	s_mov_b64 s[24:25], 0x20000
	s_mov_b32 s38, 0x20000
	s_mov_b64 s[28:29], 0x40000
	s_mov_b32 s39, 0x40000
	s_mov_b64 s[30:31], 0x60000
	s_mov_b32 s40, 0x60000
	v_mov_b32_e32 v166, 0x4000
	s_mov_b32 s35, 0
	s_movk_i32 s41, 0xc0
	v_mov_b32_e32 v167, 0x358637bd
	s_mov_b32 s42, 0x800000
	s_movk_i32 s43, 0x7ff
	s_movk_i32 s44, 0x830
	s_branch .LBB0_768
.LBB0_767:
	s_or_b64 exec, exec, s[10:11]
	v_cmp_eq_u32_e32 vcc, 0, v220
	s_and_saveexec_b64 s[10:11], vcc
	s_cbranch_execz .Lp11_tkb
	s_and_b32 s4, s2, 7
	s_lshl_b32 s4, s4, 6
	s_add_i32 s4, s4, 32
	v_mov_b32_e32 v2, s4
	v_mov_b32_e32 v1, 1
	global_atomic_add v1, v2, v1, s[100:101] sc0
	s_waitcnt vmcnt(0)
	v_mov_b32_e32 v2, 0x10608
	ds_write_b32 v2, v1
	s_waitcnt lgkmcnt(0)
.Lp11_tkb:
	s_or_b64 exec, exec, s[10:11]
	s_barrier
	v_mov_b32_e32 v1, 0x10608
	ds_read_b32 v1, v1
	s_waitcnt lgkmcnt(0)
	s_nop 1
	v_readfirstlane_b32 s4, v1
	s_nop 3
	s_lshl_b32 s4, s4, 3
	s_and_b32 s10, s2, 7
	s_or_b32 s4, s4, s10
	s_cmpk_lt_i32 s4, 0x880
	s_cbranch_scc0 .LBB0_962
